# NSA tile loop: the four V-fragment LDS reads of each half issued together into spare registers with counted waits
# baseline (speedup 1.0000x reference)
; DEVI f32x4 mfma16(bf16x8 a, bf16x8 b, f32x4 c) { return __builtin_amdgcn_mfma_f32_16x16x32_bf16(a, b, c, 0, 0, 0); }
; template <int NC>
; DEVI void pv_half(const unsigned char* Vl, int vrow, const bf16x8 (&pb)[NC], f32x4 (&o)[NC][4], int idx, int quad) {
; #pragma unroll
;   for (int dvt = 0; dvt < 4; ++dvt) {
;     const unsigned char* p = Vl + (dvt * 16 + idx) * vrow + quad * 8;
;     u32x2 lo = *(const u32x2*)p, hi = *(const u32x2*)(p + 32);
;     bf16x8 vf = as_bf8((u32x4){lo.x, lo.y, hi.x, hi.y});
; #pragma unroll
;     for (int c = 0; c < NC; ++c) o[c][dvt] = mfma16(vf, pb[c], o[c][dvt]);
;   }
; }
; template <int NC, int KS, class MaskF>
; DEVI void attn_tile(const unsigned char* Kl, int krow, const unsigned char* Vl, const bf16x8 (&q)[NC][KS], f32x4 (&o)[NC][4],
;                     float (&mr)[NC], float (&lr)[NC], int idx, int quad, int mask_mode, bool lane_ok, const MaskF& mf) {
;     ...
;     qk_half<NC, KS>(Kl + hf * 32 * krow, krow, q, s, idx, quad);
;     bf16x8 pb[NC];
; #pragma unroll
;     for (int c = 0; c < NC; ++c) {
;       if (mask_mode == 2) {
; #pragma unroll
;         for (int u = 0; u < 2; ++u)
; #pragma unroll
;           for (int j = 0; j < 4; ++j) s[c][u][j] = mf(c, hf * 32 + u * 16 + quad * 4 + j) ? s[c][u][j] : -1e30f;
;       } else if (mask_mode == 1) {
; #pragma unroll
;         for (int u = 0; u < 2; ++u)
; #pragma unroll
;           for (int j = 0; j < 4; ++j) s[c][u][j] = lane_ok ? s[c][u][j] : -1e30f;
;       }
.LBB0_1462:
	s_mul_i32 s4, s2, 0x2400
	v_cvt_pk_bf16_f32 v84, v104, v32
	v_add_u32_e32 v32, s4, v142
	v_add_u32_e32 v150, 0x6800, v32
	ds_read2_b64 v[88:91], v150 offset1:4
	v_add_u32_e32 v152, 0x7000, v32
	v_cvt_pk_bf16_f32 v85, v35, v100
	v_cvt_pk_bf16_f32 v86, v105, v34
	v_cvt_pk_bf16_f32 v87, v106, v102
	v_add_u32_e32 v153, 0x7800, v32
	v_add_u32_e32 v154, 0x8000, v32
	ds_read2_b64 v[184:187], v152 offset0:32 offset1:36
	ds_read2_b64 v[188:191], v153 offset0:64 offset1:68
	ds_read2_b64 v[192:195], v154 offset0:96 offset1:100
	s_waitcnt lgkmcnt(3)
	v_mfma_f32_16x16x32_bf16 v[80:83], v[88:91], v[92:95], v[80:83]
	v_mfma_f32_16x16x32_bf16 v[64:67], v[88:91], v[96:99], v[64:67]
	v_mfma_f32_16x16x32_bf16 v[48:51], v[88:91], v[84:87], v[48:51]
	s_waitcnt lgkmcnt(2)
	v_mfma_f32_16x16x32_bf16 v[76:79], v[184:187], v[92:95], v[76:79]
	v_mfma_f32_16x16x32_bf16 v[60:63], v[184:187], v[96:99], v[60:63]
	v_mfma_f32_16x16x32_bf16 v[44:47], v[184:187], v[84:87], v[44:47]
	s_waitcnt lgkmcnt(1)
	v_mfma_f32_16x16x32_bf16 v[72:75], v[188:191], v[92:95], v[72:75]
	v_mfma_f32_16x16x32_bf16 v[56:59], v[188:191], v[96:99], v[56:59]
	v_mfma_f32_16x16x32_bf16 v[40:43], v[188:191], v[84:87], v[40:43]
	s_waitcnt lgkmcnt(0)
	v_mfma_f32_16x16x32_bf16 v[68:71], v[192:195], v[92:95], v[68:71]
	v_mfma_f32_16x16x32_bf16 v[52:55], v[192:195], v[96:99], v[52:55]
	v_mfma_f32_16x16x32_bf16 v[34:37], v[192:195], v[84:87], v[36:39]
	ds_read_b128 v[84:87], v151 offset:4608
	ds_read_b128 v[88:91], v151 offset:4672
	v_or_b32_e32 v162, s3, v143
	v_cmp_lt_i32_e32 vcc, 1, v113
	v_or_b32_e32 v157, 18, v162
	s_waitcnt lgkmcnt(1)
	v_mfma_f32_16x16x32_bf16 v[92:95], v[84:87], v[0:3], 0
	v_mfma_f32_16x16x32_bf16 v[96:99], v[84:87], v[8:11], 0
	v_mfma_f32_16x16x32_bf16 v[84:87], v[84:87], v[16:19], 0
	s_waitcnt lgkmcnt(0)
	v_mfma_f32_16x16x32_bf16 v[92:95], v[88:91], v[4:7], v[92:95]
	v_mfma_f32_16x16x32_bf16 v[96:99], v[88:91], v[12:15], v[96:99]
	v_mfma_f32_16x16x32_bf16 v[84:87], v[88:91], v[20:23], v[84:87]
	ds_read_b128 v[88:91], v151 offset:6912
	ds_read_b128 v[132:135], v151 offset:6976
	v_or_b32_e32 v151, 19, v162
	s_waitcnt lgkmcnt(1)
	v_mfma_f32_16x16x32_bf16 v[100:103], v[88:91], v[0:3], 0
	v_mfma_f32_16x16x32_bf16 v[158:161], v[88:91], v[8:11], 0
	v_mfma_f32_16x16x32_bf16 v[88:91], v[88:91], v[16:19], 0
	s_waitcnt lgkmcnt(0)
	v_mfma_f32_16x16x32_bf16 v[104:107], v[132:135], v[4:7], v[100:103]
	v_mfma_f32_16x16x32_bf16 v[100:103], v[132:135], v[12:15], v[158:161]
	v_mfma_f32_16x16x32_bf16 v[88:91], v[132:135], v[20:23], v[88:91]
	s_nop 2
	v_or_b32_e32 v161, 2, v162
	v_or_b32_e32 v160, 3, v162
	v_or_b32_e32 v159, 16, v162
	v_or_b32_e32 v158, 17, v162
	s_and_saveexec_b64 s[4:5], vcc
	s_xor_b64 s[20:21], exec, s[4:5]
	s_cbranch_execz .LBB0_1464
	v_cmp_gt_i32_e32 vcc, v162, v125
	v_cmp_gt_i32_e64 s[4:5], v162, v149
	s_or_b64 vcc, s[0:1], vcc
	s_nop 0
	v_cndmask_b32_e64 v32, v238, v92, s[4:5]
	v_cndmask_b32_e32 v92, v32, v238, vcc
	v_cmp_lt_i32_e32 vcc, v162, v125
	v_cmp_ge_i32_e64 s[4:5], v162, v149
	s_and_b64 vcc, vcc, s[4:5]
	v_cndmask_b32_e32 v32, v238, v93, vcc
	v_cmp_gt_i32_e32 vcc, v161, v125
	v_cmp_gt_i32_e64 s[4:5], v161, v149
	v_cndmask_b32_e64 v93, v32, v238, s[0:1]
	s_or_b64 vcc, s[0:1], vcc
	v_cndmask_b32_e64 v32, v238, v94, s[4:5]
	v_cndmask_b32_e32 v94, v32, v238, vcc
	v_cmp_gt_i32_e32 vcc, v160, v125
	v_cmp_gt_i32_e64 s[4:5], v160, v149
	s_or_b64 vcc, s[0:1], vcc
	s_nop 0
	v_cndmask_b32_e64 v32, v238, v95, s[4:5]
	v_cndmask_b32_e32 v95, v32, v238, vcc
	v_cmp_gt_i32_e32 vcc, v159, v125
	v_cmp_gt_i32_e64 s[4:5], v159, v149
	s_or_b64 vcc, s[0:1], vcc
	s_nop 0
	v_cndmask_b32_e64 v32, v238, v104, s[4:5]
	v_cndmask_b32_e32 v104, v32, v238, vcc
	v_cmp_gt_i32_e32 vcc, v158, v125
	v_cmp_gt_i32_e64 s[4:5], v158, v149
	s_or_b64 vcc, s[0:1], vcc
	s_nop 0
	v_cndmask_b32_e64 v32, v238, v105, s[4:5]
	v_cndmask_b32_e32 v105, v32, v238, vcc
	v_cmp_gt_i32_e32 vcc, v157, v125
	v_cmp_gt_i32_e64 s[4:5], v157, v149
	s_or_b64 vcc, s[0:1], vcc
	s_nop 0
	v_cndmask_b32_e64 v32, v238, v106, s[4:5]
	v_cndmask_b32_e32 v106, v32, v238, vcc
	v_cmp_gt_i32_e32 vcc, v151, v125
	v_cmp_gt_i32_e64 s[4:5], v151, v149
	s_or_b64 vcc, s[0:1], vcc
	s_nop 0
	v_cndmask_b32_e64 v32, v238, v107, s[4:5]
	v_cndmask_b32_e32 v107, v32, v238, vcc

; DEVI unsigned pk2(float lo, float hi) { unsigned r; asm("v_cvt_pk_bf16_f32 %0, %1, %2" : "=v"(r) : "v"(lo), "v"(hi)); return r; }
; DEVI f32x4 mfma16(bf16x8 a, bf16x8 b, f32x4 c) { return __builtin_amdgcn_mfma_f32_16x16x32_bf16(a, b, c, 0, 0, 0); }
; template <int NC>
; DEVI void pv_half(const unsigned char* Vl, int vrow, const bf16x8 (&pb)[NC], f32x4 (&o)[NC][4], int idx, int quad) {
; #pragma unroll
;   for (int dvt = 0; dvt < 4; ++dvt) {
;     const unsigned char* p = Vl + (dvt * 16 + idx) * vrow + quad * 8;
;     u32x2 lo = *(const u32x2*)p, hi = *(const u32x2*)(p + 32);
;     bf16x8 vf = as_bf8((u32x4){lo.x, lo.y, hi.x, hi.y});
; #pragma unroll
;     for (int c = 0; c < NC; ++c) o[c][dvt] = mfma16(vf, pb[c], o[c][dvt]);
;   }
; }
; DEVI bf16x8 pack_p(const f32x4& a, const f32x4& b) { return as_bf8((u32x4){pk2(a[0], a[1]), pk2(a[2], a[3]), pk2(b[0], b[1]), pk2(b[2], b[3])}); }
.LBB0_1486:
	ds_read2_b64 v[88:91], v150 offset0:8 offset1:12
	v_cvt_pk_bf16_f32 v84, v106, v32
	v_cvt_pk_bf16_f32 v85, v39, v100
	v_cvt_pk_bf16_f32 v86, v107, v38
	v_cvt_pk_bf16_f32 v87, v113, v102
	v_add_f32_e32 v117, v117, v105
	v_add_f32_e32 v148, v148, v119
	v_add_f32_e32 v116, v104, v101
	ds_read2_b64 v[184:187], v152 offset0:40 offset1:44
	ds_read2_b64 v[188:191], v153 offset0:72 offset1:76
	ds_read2_b64 v[192:195], v154 offset0:104 offset1:108
	s_waitcnt lgkmcnt(3)
	v_mfma_f32_16x16x32_bf16 v[80:83], v[88:91], v[92:95], v[80:83]
	v_mfma_f32_16x16x32_bf16 v[64:67], v[88:91], v[96:99], v[64:67]
	v_mfma_f32_16x16x32_bf16 v[48:51], v[88:91], v[84:87], v[48:51]
	s_waitcnt lgkmcnt(2)
	v_mfma_f32_16x16x32_bf16 v[76:79], v[184:187], v[92:95], v[76:79]
	v_mfma_f32_16x16x32_bf16 v[60:63], v[184:187], v[96:99], v[60:63]
	v_mfma_f32_16x16x32_bf16 v[44:47], v[184:187], v[84:87], v[44:47]
	s_waitcnt lgkmcnt(1)
	v_mfma_f32_16x16x32_bf16 v[72:75], v[188:191], v[92:95], v[72:75]
	v_mfma_f32_16x16x32_bf16 v[56:59], v[188:191], v[96:99], v[56:59]
	v_mfma_f32_16x16x32_bf16 v[40:43], v[188:191], v[84:87], v[40:43]
	s_waitcnt lgkmcnt(0)
	v_mfma_f32_16x16x32_bf16 v[68:71], v[192:195], v[92:95], v[68:71]
	v_mfma_f32_16x16x32_bf16 v[52:55], v[192:195], v[96:99], v[52:55]
	v_mfma_f32_16x16x32_bf16 v[36:39], v[192:195], v[84:87], v[34:37]
